# P1 waves 4-7 use token groups 2,4,2 (same stagger as P7)
# baseline (speedup 1.0000x reference)
.Lp1n_norow:
	s_waitcnt lgkmcnt(0)
	s_cmp_lt_u32 s97, 4
	s_cbranch_scc0 .Lp1n_pathB
	s_add_u32 s0, s19, 0
	s_cmpk_lt_u32 s0, 0x2000
	s_cselect_b32 s2, s8, s10
	s_cselect_b32 s3, s9, s11
	s_and_b32 s1, s0, 0x1fff
	s_lshl_b32 s4, s1, 12
	s_add_u32 s2, s2, s4
	s_addc_u32 s3, s3, 0
	global_load_dwordx4 v[84:87], v52, s[2:3] offset:0 nt
	global_load_dwordx4 v[88:91], v52, s[2:3] offset:1024 nt
	global_load_dwordx4 v[92:95], v52, s[2:3] offset:2048 nt
	global_load_dwordx4 v[96:99], v52, s[2:3] offset:3072 nt
	s_cmp_eq_u32 s26, 0
	s_cbranch_scc1 .Lp1n_nocol_a0
	s_and_b32 s4, s0, 63
	s_lshl_b32 s4, s4, 10
	s_add_u32 s2, s74, 0x94000
	s_addc_u32 s3, s75, 0
	s_add_u32 s2, s2, s4
	s_addc_u32 s3, s3, 0
	global_load_dwordx4 v[148:151], v52, s[2:3]
	s_add_u32 s2, s2, 0x10000
	s_addc_u32 s3, s3, 0
	global_load_dwordx4 v[152:155], v52, s[2:3]

.Lp1n_pathB:
	s_add_u32 s0, s19, 0
	s_cmpk_lt_u32 s0, 0x2000
	s_cselect_b32 s2, s8, s10
	s_cselect_b32 s3, s9, s11
	s_and_b32 s1, s0, 0x1fff
	s_lshl_b32 s4, s1, 12
	s_add_u32 s2, s2, s4
	s_addc_u32 s3, s3, 0
	global_load_dwordx4 v[84:87], v52, s[2:3] offset:0 nt
	global_load_dwordx4 v[88:91], v52, s[2:3] offset:1024 nt
	global_load_dwordx4 v[92:95], v52, s[2:3] offset:2048 nt
	global_load_dwordx4 v[96:99], v52, s[2:3] offset:3072 nt
	s_cmp_eq_u32 s26, 0
	s_cbranch_scc1 .Lp1n_nocol_b0
	s_and_b32 s4, s0, 63
	s_lshl_b32 s4, s4, 10
	s_add_u32 s2, s74, 0x94000
	s_addc_u32 s3, s75, 0
	s_add_u32 s2, s2, s4
	s_addc_u32 s3, s3, 0
	global_load_dwordx4 v[148:151], v52, s[2:3]
	s_add_u32 s2, s2, 0x10000
	s_addc_u32 s3, s3, 0
	global_load_dwordx4 v[152:155], v52, s[2:3]
.Lp1n_nocol_b0:
	s_add_u32 s0, s19, 1
	s_cmpk_lt_u32 s0, 0x2000
	s_cselect_b32 s2, s8, s10
	s_cselect_b32 s3, s9, s11
	s_and_b32 s1, s0, 0x1fff
	s_lshl_b32 s4, s1, 12
	s_add_u32 s2, s2, s4
	s_addc_u32 s3, s3, 0
	global_load_dwordx4 v[100:103], v52, s[2:3] offset:0 nt
	global_load_dwordx4 v[104:107], v52, s[2:3] offset:1024 nt
	global_load_dwordx4 v[108:111], v52, s[2:3] offset:2048 nt
	global_load_dwordx4 v[112:115], v52, s[2:3] offset:3072 nt
	s_cmp_eq_u32 s26, 0
	s_cbranch_scc1 .Lp1n_nocol_b1
	s_and_b32 s4, s0, 63
	s_lshl_b32 s4, s4, 10
	s_add_u32 s2, s74, 0x94000
	s_addc_u32 s3, s75, 0
	s_add_u32 s2, s2, s4
	s_addc_u32 s3, s3, 0
	global_load_dwordx4 v[156:159], v52, s[2:3]
	s_add_u32 s2, s2, 0x10000
	s_addc_u32 s3, s3, 0
	global_load_dwordx4 v[160:163], v52, s[2:3]
.Lp1n_nocol_b1:
	s_waitcnt vmcnt(0)
	s_cmp_eq_u32 s26, 0
	s_cbranch_scc1 .Lp1n_nope_b0
	v_pk_add_f32 v[84:85], v[84:85], v[180:181]
	v_pk_add_f32 v[86:87], v[86:87], v[182:183]
	v_pk_add_f32 v[88:89], v[88:89], v[184:185]
	v_pk_add_f32 v[90:91], v[90:91], v[186:187]
	v_pk_add_f32 v[92:93], v[92:93], v[148:149]
	v_pk_add_f32 v[94:95], v[94:95], v[150:151]
	v_pk_add_f32 v[96:97], v[96:97], v[152:153]
	v_pk_add_f32 v[98:99], v[98:99], v[154:155]
	v_pk_add_f32 v[100:101], v[100:101], v[180:181]
	v_pk_add_f32 v[102:103], v[102:103], v[182:183]
	v_pk_add_f32 v[104:105], v[104:105], v[184:185]
	v_pk_add_f32 v[106:107], v[106:107], v[186:187]
	v_pk_add_f32 v[108:109], v[108:109], v[156:157]
	v_pk_add_f32 v[110:111], v[110:111], v[158:159]
	v_pk_add_f32 v[112:113], v[112:113], v[160:161]
	v_pk_add_f32 v[114:115], v[114:115], v[162:163]
.Lp1n_nope_b0:
	v_pk_mul_f32 v[34:35], v[84:85], v[84:85]
	v_pk_mul_f32 v[36:37], v[100:101], v[100:101]
	v_pk_fma_f32 v[34:35], v[86:87], v[86:87], v[34:35]
	v_pk_fma_f32 v[36:37], v[102:103], v[102:103], v[36:37]
	v_pk_fma_f32 v[34:35], v[88:89], v[88:89], v[34:35]
	v_pk_fma_f32 v[36:37], v[104:105], v[104:105], v[36:37]
	v_pk_fma_f32 v[34:35], v[90:91], v[90:91], v[34:35]
	v_pk_fma_f32 v[36:37], v[106:107], v[106:107], v[36:37]
	v_pk_fma_f32 v[34:35], v[92:93], v[92:93], v[34:35]
	v_pk_fma_f32 v[36:37], v[108:109], v[108:109], v[36:37]
	v_pk_fma_f32 v[34:35], v[94:95], v[94:95], v[34:35]
	v_pk_fma_f32 v[36:37], v[110:111], v[110:111], v[36:37]
	v_pk_fma_f32 v[34:35], v[96:97], v[96:97], v[34:35]
	v_pk_fma_f32 v[36:37], v[112:113], v[112:113], v[36:37]
	v_pk_fma_f32 v[34:35], v[98:99], v[98:99], v[34:35]
	v_pk_fma_f32 v[36:37], v[114:115], v[114:115], v[36:37]
	v_add_f32_e32 v34, v34, v35
	v_add_f32_e32 v36, v36, v37
	ds_bpermute_b32 v35, v51, v34
	ds_bpermute_b32 v37, v51, v36
	s_waitcnt lgkmcnt(0)
	v_add_f32_e32 v34, v34, v35
	v_add_f32_e32 v36, v36, v37
	ds_bpermute_b32 v35, v66, v34
	ds_bpermute_b32 v37, v66, v36
	s_waitcnt lgkmcnt(0)
	v_add_f32_e32 v34, v34, v35
	v_add_f32_e32 v36, v36, v37
	ds_bpermute_b32 v35, v67, v34
	ds_bpermute_b32 v37, v67, v36
	s_waitcnt lgkmcnt(0)
	v_add_f32_e32 v34, v34, v35
	v_add_f32_e32 v36, v36, v37
	ds_bpermute_b32 v35, v68, v34
	ds_bpermute_b32 v37, v68, v36
	s_waitcnt lgkmcnt(0)
	v_add_f32_e32 v34, v34, v35
	v_add_f32_e32 v36, v36, v37
	ds_bpermute_b32 v35, v69, v34
	ds_bpermute_b32 v37, v69, v36
	s_waitcnt lgkmcnt(0)
	v_add_f32_e32 v34, v34, v35
	v_add_f32_e32 v36, v36, v37
	ds_bpermute_b32 v35, v70, v34
	ds_bpermute_b32 v37, v70, v36
	s_waitcnt lgkmcnt(0)
	v_add_f32_e32 v34, v34, v35
	v_add_f32_e32 v36, v36, v37
	v_fmamk_f32 v34, v34, 0x3a800000, v74
	v_fmamk_f32 v36, v36, 0x3a800000, v74
	v_mul_f32_e32 v75, 0x4b800000, v34
	v_cmp_gt_f32_e32 vcc, s24, v34
	s_nop 1
	v_cndmask_b32_e32 v34, v34, v75, vcc
	v_rsq_f32_e32 v34, v34
	s_nop 0
	v_mul_f32_e32 v75, 0x45800000, v34
	v_cndmask_b32_e32 v34, v34, v75, vcc
	v_mov_b32_e32 v35, 0
	v_mul_f32_e32 v75, 0x4b800000, v36
	v_cmp_gt_f32_e32 vcc, s24, v36
	s_nop 1
	v_cndmask_b32_e32 v36, v36, v75, vcc
	v_rsq_f32_e32 v36, v36
	s_nop 0
	v_mul_f32_e32 v75, 0x45800000, v36
	v_cndmask_b32_e32 v36, v36, v75, vcc
	v_mov_b32_e32 v37, 0
	s_add_u32 s0, s19, 0
	s_lshl_b32 s0, s0, 11
	s_add_u32 s2, s72, s0
	s_addc_u32 s3, s73, 0
	v_pk_mul_f32 v[84:85], v[84:85], v[34:35] op_sel_hi:[1,0]
	v_pk_mul_f32 v[86:87], v[86:87], v[34:35] op_sel_hi:[1,0]
	v_pk_fma_f32 v[84:85], v[2:3], v[84:85], v[10:11]
	v_pk_fma_f32 v[86:87], v[4:5], v[86:87], v[12:13]
	v_cvt_pk_bf16_f32 v84, v84, v85
	v_cvt_pk_bf16_f32 v85, v86, v87
	global_store_dwordx2 v78, v[84:85], s[2:3] offset:0
	v_pk_mul_f32 v[88:89], v[88:89], v[34:35] op_sel_hi:[1,0]
	v_pk_mul_f32 v[90:91], v[90:91], v[34:35] op_sel_hi:[1,0]
	v_pk_fma_f32 v[88:89], v[6:7], v[88:89], v[14:15]
	v_pk_fma_f32 v[90:91], v[8:9], v[90:91], v[16:17]
	v_cvt_pk_bf16_f32 v88, v88, v89
	v_cvt_pk_bf16_f32 v89, v90, v91
	global_store_dwordx2 v78, v[88:89], s[2:3] offset:512
	v_pk_mul_f32 v[92:93], v[92:93], v[34:35] op_sel_hi:[1,0]
	v_pk_mul_f32 v[94:95], v[94:95], v[34:35] op_sel_hi:[1,0]
	v_pk_fma_f32 v[92:93], v[18:19], v[92:93], v[26:27]
	v_pk_fma_f32 v[94:95], v[20:21], v[94:95], v[28:29]
	v_cvt_pk_bf16_f32 v92, v92, v93
	v_cvt_pk_bf16_f32 v93, v94, v95
	global_store_dwordx2 v78, v[92:93], s[2:3] offset:1024
	v_pk_mul_f32 v[96:97], v[96:97], v[34:35] op_sel_hi:[1,0]
	v_pk_mul_f32 v[98:99], v[98:99], v[34:35] op_sel_hi:[1,0]
	v_pk_fma_f32 v[96:97], v[22:23], v[96:97], v[30:31]
	v_pk_fma_f32 v[98:99], v[24:25], v[98:99], v[32:33]
	v_cvt_pk_bf16_f32 v96, v96, v97
	v_cvt_pk_bf16_f32 v97, v98, v99
	global_store_dwordx2 v78, v[96:97], s[2:3] offset:1536
	s_add_u32 s0, s19, 1
	s_lshl_b32 s0, s0, 11
	s_add_u32 s2, s72, s0
	s_addc_u32 s3, s73, 0
	v_pk_mul_f32 v[100:101], v[100:101], v[36:37] op_sel_hi:[1,0]
	v_pk_mul_f32 v[102:103], v[102:103], v[36:37] op_sel_hi:[1,0]
	v_pk_fma_f32 v[100:101], v[2:3], v[100:101], v[10:11]
	v_pk_fma_f32 v[102:103], v[4:5], v[102:103], v[12:13]
	v_cvt_pk_bf16_f32 v100, v100, v101
	v_cvt_pk_bf16_f32 v101, v102, v103
	global_store_dwordx2 v78, v[100:101], s[2:3] offset:0
	v_pk_mul_f32 v[104:105], v[104:105], v[36:37] op_sel_hi:[1,0]
	v_pk_mul_f32 v[106:107], v[106:107], v[36:37] op_sel_hi:[1,0]
	v_pk_fma_f32 v[104:105], v[6:7], v[104:105], v[14:15]
	v_pk_fma_f32 v[106:107], v[8:9], v[106:107], v[16:17]
	v_cvt_pk_bf16_f32 v104, v104, v105
	v_cvt_pk_bf16_f32 v105, v106, v107
	global_store_dwordx2 v78, v[104:105], s[2:3] offset:512
	v_pk_mul_f32 v[108:109], v[108:109], v[36:37] op_sel_hi:[1,0]
	v_pk_mul_f32 v[110:111], v[110:111], v[36:37] op_sel_hi:[1,0]
	v_pk_fma_f32 v[108:109], v[18:19], v[108:109], v[26:27]
	v_pk_fma_f32 v[110:111], v[20:21], v[110:111], v[28:29]
	v_cvt_pk_bf16_f32 v108, v108, v109
	v_cvt_pk_bf16_f32 v109, v110, v111
	global_store_dwordx2 v78, v[108:109], s[2:3] offset:1024
	v_pk_mul_f32 v[112:113], v[112:113], v[36:37] op_sel_hi:[1,0]
	v_pk_mul_f32 v[114:115], v[114:115], v[36:37] op_sel_hi:[1,0]
	v_pk_fma_f32 v[112:113], v[22:23], v[112:113], v[30:31]
	v_pk_fma_f32 v[114:115], v[24:25], v[114:115], v[32:33]
	v_cvt_pk_bf16_f32 v112, v112, v113
	v_cvt_pk_bf16_f32 v113, v114, v115
	global_store_dwordx2 v78, v[112:113], s[2:3] offset:1536
	s_nop 1
	s_add_u32 s0, s19, 2
	s_cmpk_lt_u32 s0, 0x2000
	s_cselect_b32 s2, s8, s10
	s_cselect_b32 s3, s9, s11
	s_and_b32 s1, s0, 0x1fff
	s_lshl_b32 s4, s1, 12
	s_add_u32 s2, s2, s4
	s_addc_u32 s3, s3, 0
	global_load_dwordx4 v[84:87], v52, s[2:3] offset:0 nt
	global_load_dwordx4 v[88:91], v52, s[2:3] offset:1024 nt
	global_load_dwordx4 v[92:95], v52, s[2:3] offset:2048 nt
	global_load_dwordx4 v[96:99], v52, s[2:3] offset:3072 nt
	s_cmp_eq_u32 s26, 0
	s_cbranch_scc1 .Lp1n_nocol_b2
	s_and_b32 s4, s0, 63
	s_lshl_b32 s4, s4, 10
	s_add_u32 s2, s74, 0x94000
	s_addc_u32 s3, s75, 0
	s_add_u32 s2, s2, s4
	s_addc_u32 s3, s3, 0
	global_load_dwordx4 v[148:151], v52, s[2:3]
	s_add_u32 s2, s2, 0x10000
	s_addc_u32 s3, s3, 0
	global_load_dwordx4 v[152:155], v52, s[2:3]
.Lp1n_nocol_b2:
	s_add_u32 s0, s19, 3
	s_cmpk_lt_u32 s0, 0x2000
	s_cselect_b32 s2, s8, s10
	s_cselect_b32 s3, s9, s11
	s_and_b32 s1, s0, 0x1fff
	s_lshl_b32 s4, s1, 12
	s_add_u32 s2, s2, s4
	s_addc_u32 s3, s3, 0
	global_load_dwordx4 v[100:103], v52, s[2:3] offset:0 nt
	global_load_dwordx4 v[104:107], v52, s[2:3] offset:1024 nt
	global_load_dwordx4 v[108:111], v52, s[2:3] offset:2048 nt
	global_load_dwordx4 v[112:115], v52, s[2:3] offset:3072 nt
	s_cmp_eq_u32 s26, 0
	s_cbranch_scc1 .Lp1n_nocol_b3
	s_and_b32 s4, s0, 63
	s_lshl_b32 s4, s4, 10
	s_add_u32 s2, s74, 0x94000
	s_addc_u32 s3, s75, 0
	s_add_u32 s2, s2, s4
	s_addc_u32 s3, s3, 0
	global_load_dwordx4 v[156:159], v52, s[2:3]
	s_add_u32 s2, s2, 0x10000
	s_addc_u32 s3, s3, 0
	global_load_dwordx4 v[160:163], v52, s[2:3]
.Lp1n_nocol_b3:
	s_add_u32 s0, s19, 4
	s_cmpk_lt_u32 s0, 0x2000
	s_cselect_b32 s2, s8, s10
	s_cselect_b32 s3, s9, s11
	s_and_b32 s1, s0, 0x1fff
	s_lshl_b32 s4, s1, 12
	s_add_u32 s2, s2, s4
	s_addc_u32 s3, s3, 0
	global_load_dwordx4 v[116:119], v52, s[2:3] offset:0 nt
	global_load_dwordx4 v[120:123], v52, s[2:3] offset:1024 nt
	global_load_dwordx4 v[124:127], v52, s[2:3] offset:2048 nt
	global_load_dwordx4 v[128:131], v52, s[2:3] offset:3072 nt
	s_cmp_eq_u32 s26, 0
	s_cbranch_scc1 .Lp1n_nocol_b4
	s_and_b32 s4, s0, 63
	s_lshl_b32 s4, s4, 10
	s_add_u32 s2, s74, 0x94000
	s_addc_u32 s3, s75, 0
	s_add_u32 s2, s2, s4
	s_addc_u32 s3, s3, 0
	global_load_dwordx4 v[164:167], v52, s[2:3]
	s_add_u32 s2, s2, 0x10000
	s_addc_u32 s3, s3, 0
	global_load_dwordx4 v[168:171], v52, s[2:3]
.Lp1n_nocol_b4:
	s_add_u32 s0, s19, 5
	s_cmpk_lt_u32 s0, 0x2000
	s_cselect_b32 s2, s8, s10
	s_cselect_b32 s3, s9, s11
	s_and_b32 s1, s0, 0x1fff
	s_lshl_b32 s4, s1, 12
	s_add_u32 s2, s2, s4
	s_addc_u32 s3, s3, 0
	global_load_dwordx4 v[132:135], v52, s[2:3] offset:0 nt
	global_load_dwordx4 v[136:139], v52, s[2:3] offset:1024 nt
	global_load_dwordx4 v[140:143], v52, s[2:3] offset:2048 nt
	global_load_dwordx4 v[144:147], v52, s[2:3] offset:3072 nt
	s_cmp_eq_u32 s26, 0
	s_cbranch_scc1 .Lp1n_nocol_b5
	s_and_b32 s4, s0, 63
	s_lshl_b32 s4, s4, 10
	s_add_u32 s2, s74, 0x94000
	s_addc_u32 s3, s75, 0
	s_add_u32 s2, s2, s4
	s_addc_u32 s3, s3, 0
	global_load_dwordx4 v[172:175], v52, s[2:3]
	s_add_u32 s2, s2, 0x10000
	s_addc_u32 s3, s3, 0
	global_load_dwordx4 v[176:179], v52, s[2:3]

.Lp1n_nope_b1:
	v_pk_mul_f32 v[34:35], v[84:85], v[84:85]
	v_pk_mul_f32 v[36:37], v[100:101], v[100:101]
	v_pk_mul_f32 v[38:39], v[116:117], v[116:117]
	v_pk_mul_f32 v[40:41], v[132:133], v[132:133]
	v_pk_fma_f32 v[34:35], v[86:87], v[86:87], v[34:35]
	v_pk_fma_f32 v[36:37], v[102:103], v[102:103], v[36:37]
	v_pk_fma_f32 v[38:39], v[118:119], v[118:119], v[38:39]
	v_pk_fma_f32 v[40:41], v[134:135], v[134:135], v[40:41]
	v_pk_fma_f32 v[34:35], v[88:89], v[88:89], v[34:35]
	v_pk_fma_f32 v[36:37], v[104:105], v[104:105], v[36:37]
	v_pk_fma_f32 v[38:39], v[120:121], v[120:121], v[38:39]
	v_pk_fma_f32 v[40:41], v[136:137], v[136:137], v[40:41]
	v_pk_fma_f32 v[34:35], v[90:91], v[90:91], v[34:35]
	v_pk_fma_f32 v[36:37], v[106:107], v[106:107], v[36:37]
	v_pk_fma_f32 v[38:39], v[122:123], v[122:123], v[38:39]
	v_pk_fma_f32 v[40:41], v[138:139], v[138:139], v[40:41]
	v_pk_fma_f32 v[34:35], v[92:93], v[92:93], v[34:35]
	v_pk_fma_f32 v[36:37], v[108:109], v[108:109], v[36:37]
	v_pk_fma_f32 v[38:39], v[124:125], v[124:125], v[38:39]
	v_pk_fma_f32 v[40:41], v[140:141], v[140:141], v[40:41]
	v_pk_fma_f32 v[34:35], v[94:95], v[94:95], v[34:35]
	v_pk_fma_f32 v[36:37], v[110:111], v[110:111], v[36:37]
	v_pk_fma_f32 v[38:39], v[126:127], v[126:127], v[38:39]
	v_pk_fma_f32 v[40:41], v[142:143], v[142:143], v[40:41]
	v_pk_fma_f32 v[34:35], v[96:97], v[96:97], v[34:35]
	v_pk_fma_f32 v[36:37], v[112:113], v[112:113], v[36:37]
	v_pk_fma_f32 v[38:39], v[128:129], v[128:129], v[38:39]
	v_pk_fma_f32 v[40:41], v[144:145], v[144:145], v[40:41]
	v_pk_fma_f32 v[34:35], v[98:99], v[98:99], v[34:35]
	v_pk_fma_f32 v[36:37], v[114:115], v[114:115], v[36:37]
	v_pk_fma_f32 v[38:39], v[130:131], v[130:131], v[38:39]
	v_pk_fma_f32 v[40:41], v[146:147], v[146:147], v[40:41]
	v_add_f32_e32 v34, v34, v35
	v_add_f32_e32 v36, v36, v37
	v_add_f32_e32 v38, v38, v39
	v_add_f32_e32 v40, v40, v41
	ds_bpermute_b32 v35, v51, v34
	ds_bpermute_b32 v37, v51, v36
	ds_bpermute_b32 v39, v51, v38
	ds_bpermute_b32 v41, v51, v40
	s_waitcnt lgkmcnt(0)
	v_add_f32_e32 v34, v34, v35
	v_add_f32_e32 v36, v36, v37
	v_add_f32_e32 v38, v38, v39
	v_add_f32_e32 v40, v40, v41
	ds_bpermute_b32 v35, v66, v34
	ds_bpermute_b32 v37, v66, v36
	ds_bpermute_b32 v39, v66, v38
	ds_bpermute_b32 v41, v66, v40
	s_waitcnt lgkmcnt(0)
	v_add_f32_e32 v34, v34, v35
	v_add_f32_e32 v36, v36, v37
	v_add_f32_e32 v38, v38, v39
	v_add_f32_e32 v40, v40, v41
	ds_bpermute_b32 v35, v67, v34
	ds_bpermute_b32 v37, v67, v36
	ds_bpermute_b32 v39, v67, v38
	ds_bpermute_b32 v41, v67, v40
	s_waitcnt lgkmcnt(0)
	v_add_f32_e32 v34, v34, v35
	v_add_f32_e32 v36, v36, v37
	v_add_f32_e32 v38, v38, v39
	v_add_f32_e32 v40, v40, v41
	ds_bpermute_b32 v35, v68, v34
	ds_bpermute_b32 v37, v68, v36
	ds_bpermute_b32 v39, v68, v38
	ds_bpermute_b32 v41, v68, v40
	s_waitcnt lgkmcnt(0)
	v_add_f32_e32 v34, v34, v35
	v_add_f32_e32 v36, v36, v37
	v_add_f32_e32 v38, v38, v39
	v_add_f32_e32 v40, v40, v41
	ds_bpermute_b32 v35, v69, v34
	ds_bpermute_b32 v37, v69, v36
	ds_bpermute_b32 v39, v69, v38
	ds_bpermute_b32 v41, v69, v40
	s_waitcnt lgkmcnt(0)
	v_add_f32_e32 v34, v34, v35
	v_add_f32_e32 v36, v36, v37
	v_add_f32_e32 v38, v38, v39
	v_add_f32_e32 v40, v40, v41
	ds_bpermute_b32 v35, v70, v34
	ds_bpermute_b32 v37, v70, v36
	ds_bpermute_b32 v39, v70, v38
	ds_bpermute_b32 v41, v70, v40
	s_waitcnt lgkmcnt(0)
	v_add_f32_e32 v34, v34, v35
	v_add_f32_e32 v36, v36, v37
	v_add_f32_e32 v38, v38, v39
	v_add_f32_e32 v40, v40, v41
	v_fmamk_f32 v34, v34, 0x3a800000, v74
	v_fmamk_f32 v36, v36, 0x3a800000, v74
	v_fmamk_f32 v38, v38, 0x3a800000, v74
	v_fmamk_f32 v40, v40, 0x3a800000, v74
	v_mul_f32_e32 v75, 0x4b800000, v34
	v_cmp_gt_f32_e32 vcc, s24, v34
	s_nop 1
	v_cndmask_b32_e32 v34, v34, v75, vcc
	v_rsq_f32_e32 v34, v34
	s_nop 0
	v_mul_f32_e32 v75, 0x45800000, v34
	v_cndmask_b32_e32 v34, v34, v75, vcc
	v_mov_b32_e32 v35, 0
	v_mul_f32_e32 v75, 0x4b800000, v36
	v_cmp_gt_f32_e32 vcc, s24, v36
	s_nop 1
	v_cndmask_b32_e32 v36, v36, v75, vcc
	v_rsq_f32_e32 v36, v36
	s_nop 0
	v_mul_f32_e32 v75, 0x45800000, v36
	v_cndmask_b32_e32 v36, v36, v75, vcc
	v_mov_b32_e32 v37, 0
	v_mul_f32_e32 v75, 0x4b800000, v38
	v_cmp_gt_f32_e32 vcc, s24, v38
	s_nop 1
	v_cndmask_b32_e32 v38, v38, v75, vcc
	v_rsq_f32_e32 v38, v38
	s_nop 0
	v_mul_f32_e32 v75, 0x45800000, v38
	v_cndmask_b32_e32 v38, v38, v75, vcc
	v_mov_b32_e32 v39, 0
	v_mul_f32_e32 v75, 0x4b800000, v40
	v_cmp_gt_f32_e32 vcc, s24, v40
	s_nop 1
	v_cndmask_b32_e32 v40, v40, v75, vcc
	v_rsq_f32_e32 v40, v40
	s_nop 0
	v_mul_f32_e32 v75, 0x45800000, v40
	v_cndmask_b32_e32 v40, v40, v75, vcc
	v_mov_b32_e32 v41, 0
	s_add_u32 s0, s19, 2
	s_lshl_b32 s0, s0, 11
	s_add_u32 s2, s72, s0
	s_addc_u32 s3, s73, 0
	v_pk_mul_f32 v[84:85], v[84:85], v[34:35] op_sel_hi:[1,0]
	v_pk_mul_f32 v[86:87], v[86:87], v[34:35] op_sel_hi:[1,0]
	v_pk_fma_f32 v[84:85], v[2:3], v[84:85], v[10:11]
	v_pk_fma_f32 v[86:87], v[4:5], v[86:87], v[12:13]
	v_cvt_pk_bf16_f32 v84, v84, v85
	v_cvt_pk_bf16_f32 v85, v86, v87
	global_store_dwordx2 v78, v[84:85], s[2:3] offset:0
	v_pk_mul_f32 v[88:89], v[88:89], v[34:35] op_sel_hi:[1,0]
	v_pk_mul_f32 v[90:91], v[90:91], v[34:35] op_sel_hi:[1,0]
	v_pk_fma_f32 v[88:89], v[6:7], v[88:89], v[14:15]
	v_pk_fma_f32 v[90:91], v[8:9], v[90:91], v[16:17]
	v_cvt_pk_bf16_f32 v88, v88, v89
	v_cvt_pk_bf16_f32 v89, v90, v91
	global_store_dwordx2 v78, v[88:89], s[2:3] offset:512
	v_pk_mul_f32 v[92:93], v[92:93], v[34:35] op_sel_hi:[1,0]
	v_pk_mul_f32 v[94:95], v[94:95], v[34:35] op_sel_hi:[1,0]
	v_pk_fma_f32 v[92:93], v[18:19], v[92:93], v[26:27]
	v_pk_fma_f32 v[94:95], v[20:21], v[94:95], v[28:29]
	v_cvt_pk_bf16_f32 v92, v92, v93
	v_cvt_pk_bf16_f32 v93, v94, v95
	global_store_dwordx2 v78, v[92:93], s[2:3] offset:1024
	v_pk_mul_f32 v[96:97], v[96:97], v[34:35] op_sel_hi:[1,0]
	v_pk_mul_f32 v[98:99], v[98:99], v[34:35] op_sel_hi:[1,0]
	v_pk_fma_f32 v[96:97], v[22:23], v[96:97], v[30:31]
	v_pk_fma_f32 v[98:99], v[24:25], v[98:99], v[32:33]
	v_cvt_pk_bf16_f32 v96, v96, v97
	v_cvt_pk_bf16_f32 v97, v98, v99
	global_store_dwordx2 v78, v[96:97], s[2:3] offset:1536
	s_add_u32 s0, s19, 3
	s_lshl_b32 s0, s0, 11
	s_add_u32 s2, s72, s0
	s_addc_u32 s3, s73, 0
	v_pk_mul_f32 v[100:101], v[100:101], v[36:37] op_sel_hi:[1,0]
	v_pk_mul_f32 v[102:103], v[102:103], v[36:37] op_sel_hi:[1,0]
	v_pk_fma_f32 v[100:101], v[2:3], v[100:101], v[10:11]
	v_pk_fma_f32 v[102:103], v[4:5], v[102:103], v[12:13]
	v_cvt_pk_bf16_f32 v100, v100, v101
	v_cvt_pk_bf16_f32 v101, v102, v103
	global_store_dwordx2 v78, v[100:101], s[2:3] offset:0
	v_pk_mul_f32 v[104:105], v[104:105], v[36:37] op_sel_hi:[1,0]
	v_pk_mul_f32 v[106:107], v[106:107], v[36:37] op_sel_hi:[1,0]
	v_pk_fma_f32 v[104:105], v[6:7], v[104:105], v[14:15]
	v_pk_fma_f32 v[106:107], v[8:9], v[106:107], v[16:17]
	v_cvt_pk_bf16_f32 v104, v104, v105
	v_cvt_pk_bf16_f32 v105, v106, v107
	global_store_dwordx2 v78, v[104:105], s[2:3] offset:512
	v_pk_mul_f32 v[108:109], v[108:109], v[36:37] op_sel_hi:[1,0]
	v_pk_mul_f32 v[110:111], v[110:111], v[36:37] op_sel_hi:[1,0]
	v_pk_fma_f32 v[108:109], v[18:19], v[108:109], v[26:27]
	v_pk_fma_f32 v[110:111], v[20:21], v[110:111], v[28:29]
	v_cvt_pk_bf16_f32 v108, v108, v109
	v_cvt_pk_bf16_f32 v109, v110, v111
	global_store_dwordx2 v78, v[108:109], s[2:3] offset:1024
	v_pk_mul_f32 v[112:113], v[112:113], v[36:37] op_sel_hi:[1,0]
	v_pk_mul_f32 v[114:115], v[114:115], v[36:37] op_sel_hi:[1,0]
	v_pk_fma_f32 v[112:113], v[22:23], v[112:113], v[30:31]
	v_pk_fma_f32 v[114:115], v[24:25], v[114:115], v[32:33]
	v_cvt_pk_bf16_f32 v112, v112, v113
	v_cvt_pk_bf16_f32 v113, v114, v115
	global_store_dwordx2 v78, v[112:113], s[2:3] offset:1536
	s_add_u32 s0, s19, 4
	s_lshl_b32 s0, s0, 11
	s_add_u32 s2, s72, s0
	s_addc_u32 s3, s73, 0
	v_pk_mul_f32 v[116:117], v[116:117], v[38:39] op_sel_hi:[1,0]
	v_pk_mul_f32 v[118:119], v[118:119], v[38:39] op_sel_hi:[1,0]
	v_pk_fma_f32 v[116:117], v[2:3], v[116:117], v[10:11]
	v_pk_fma_f32 v[118:119], v[4:5], v[118:119], v[12:13]
	v_cvt_pk_bf16_f32 v116, v116, v117
	v_cvt_pk_bf16_f32 v117, v118, v119
	global_store_dwordx2 v78, v[116:117], s[2:3] offset:0
	v_pk_mul_f32 v[120:121], v[120:121], v[38:39] op_sel_hi:[1,0]
	v_pk_mul_f32 v[122:123], v[122:123], v[38:39] op_sel_hi:[1,0]
	v_pk_fma_f32 v[120:121], v[6:7], v[120:121], v[14:15]
	v_pk_fma_f32 v[122:123], v[8:9], v[122:123], v[16:17]
	v_cvt_pk_bf16_f32 v120, v120, v121
	v_cvt_pk_bf16_f32 v121, v122, v123
	global_store_dwordx2 v78, v[120:121], s[2:3] offset:512
	v_pk_mul_f32 v[124:125], v[124:125], v[38:39] op_sel_hi:[1,0]
	v_pk_mul_f32 v[126:127], v[126:127], v[38:39] op_sel_hi:[1,0]
	v_pk_fma_f32 v[124:125], v[18:19], v[124:125], v[26:27]
	v_pk_fma_f32 v[126:127], v[20:21], v[126:127], v[28:29]
	v_cvt_pk_bf16_f32 v124, v124, v125
	v_cvt_pk_bf16_f32 v125, v126, v127
	global_store_dwordx2 v78, v[124:125], s[2:3] offset:1024
	v_pk_mul_f32 v[128:129], v[128:129], v[38:39] op_sel_hi:[1,0]
	v_pk_mul_f32 v[130:131], v[130:131], v[38:39] op_sel_hi:[1,0]
	v_pk_fma_f32 v[128:129], v[22:23], v[128:129], v[30:31]
	v_pk_fma_f32 v[130:131], v[24:25], v[130:131], v[32:33]
	v_cvt_pk_bf16_f32 v128, v128, v129
	v_cvt_pk_bf16_f32 v129, v130, v131
	global_store_dwordx2 v78, v[128:129], s[2:3] offset:1536
	s_add_u32 s0, s19, 5
	s_lshl_b32 s0, s0, 11
	s_add_u32 s2, s72, s0
	s_addc_u32 s3, s73, 0
	v_pk_mul_f32 v[132:133], v[132:133], v[40:41] op_sel_hi:[1,0]
	v_pk_mul_f32 v[134:135], v[134:135], v[40:41] op_sel_hi:[1,0]
	v_pk_fma_f32 v[132:133], v[2:3], v[132:133], v[10:11]
	v_pk_fma_f32 v[134:135], v[4:5], v[134:135], v[12:13]
	v_cvt_pk_bf16_f32 v132, v132, v133
	v_cvt_pk_bf16_f32 v133, v134, v135
	global_store_dwordx2 v78, v[132:133], s[2:3] offset:0
	v_pk_mul_f32 v[136:137], v[136:137], v[40:41] op_sel_hi:[1,0]
	v_pk_mul_f32 v[138:139], v[138:139], v[40:41] op_sel_hi:[1,0]
	v_pk_fma_f32 v[136:137], v[6:7], v[136:137], v[14:15]
	v_pk_fma_f32 v[138:139], v[8:9], v[138:139], v[16:17]
	v_cvt_pk_bf16_f32 v136, v136, v137
	v_cvt_pk_bf16_f32 v137, v138, v139
	global_store_dwordx2 v78, v[136:137], s[2:3] offset:512
	v_pk_mul_f32 v[140:141], v[140:141], v[40:41] op_sel_hi:[1,0]
	v_pk_mul_f32 v[142:143], v[142:143], v[40:41] op_sel_hi:[1,0]
	v_pk_fma_f32 v[140:141], v[18:19], v[140:141], v[26:27]
	v_pk_fma_f32 v[142:143], v[20:21], v[142:143], v[28:29]
	v_cvt_pk_bf16_f32 v140, v140, v141
	v_cvt_pk_bf16_f32 v141, v142, v143
	global_store_dwordx2 v78, v[140:141], s[2:3] offset:1024
	v_pk_mul_f32 v[144:145], v[144:145], v[40:41] op_sel_hi:[1,0]
	v_pk_mul_f32 v[146:147], v[146:147], v[40:41] op_sel_hi:[1,0]
	v_pk_fma_f32 v[144:145], v[22:23], v[144:145], v[30:31]
	v_pk_fma_f32 v[146:147], v[24:25], v[146:147], v[32:33]
	v_cvt_pk_bf16_f32 v144, v144, v145
	v_cvt_pk_bf16_f32 v145, v146, v147
	global_store_dwordx2 v78, v[144:145], s[2:3] offset:1536
	s_nop 1
	s_add_u32 s0, s19, 6
	s_cmpk_lt_u32 s0, 0x2000
	s_cselect_b32 s2, s8, s10
	s_cselect_b32 s3, s9, s11
	s_and_b32 s1, s0, 0x1fff
	s_lshl_b32 s4, s1, 12
	s_add_u32 s2, s2, s4
	s_addc_u32 s3, s3, 0
	global_load_dwordx4 v[84:87], v52, s[2:3] offset:0 nt
	global_load_dwordx4 v[88:91], v52, s[2:3] offset:1024 nt
	global_load_dwordx4 v[92:95], v52, s[2:3] offset:2048 nt
	global_load_dwordx4 v[96:99], v52, s[2:3] offset:3072 nt
	s_cmp_eq_u32 s26, 0
	s_cbranch_scc1 .Lp1n_nocol_b6
	s_and_b32 s4, s0, 63
	s_lshl_b32 s4, s4, 10
	s_add_u32 s2, s74, 0x94000
	s_addc_u32 s3, s75, 0
	s_add_u32 s2, s2, s4
	s_addc_u32 s3, s3, 0
	global_load_dwordx4 v[148:151], v52, s[2:3]
	s_add_u32 s2, s2, 0x10000
	s_addc_u32 s3, s3, 0
	global_load_dwordx4 v[152:155], v52, s[2:3]
.Lp1n_nocol_b6:
	s_add_u32 s0, s19, 7
	s_cmpk_lt_u32 s0, 0x2000
	s_cselect_b32 s2, s8, s10
	s_cselect_b32 s3, s9, s11
	s_and_b32 s1, s0, 0x1fff
	s_lshl_b32 s4, s1, 12
	s_add_u32 s2, s2, s4
	s_addc_u32 s3, s3, 0
	global_load_dwordx4 v[100:103], v52, s[2:3] offset:0 nt
	global_load_dwordx4 v[104:107], v52, s[2:3] offset:1024 nt
	global_load_dwordx4 v[108:111], v52, s[2:3] offset:2048 nt
	global_load_dwordx4 v[112:115], v52, s[2:3] offset:3072 nt
	s_cmp_eq_u32 s26, 0
	s_cbranch_scc1 .Lp1n_nocol_b7
	s_and_b32 s4, s0, 63
	s_lshl_b32 s4, s4, 10
	s_add_u32 s2, s74, 0x94000
	s_addc_u32 s3, s75, 0
	s_add_u32 s2, s2, s4
	s_addc_u32 s3, s3, 0
	global_load_dwordx4 v[156:159], v52, s[2:3]
	s_add_u32 s2, s2, 0x10000
	s_addc_u32 s3, s3, 0
	global_load_dwordx4 v[160:163], v52, s[2:3]

.Lp1n_nope_b2:
	v_pk_mul_f32 v[34:35], v[84:85], v[84:85]
	v_pk_mul_f32 v[36:37], v[100:101], v[100:101]
	v_pk_fma_f32 v[34:35], v[86:87], v[86:87], v[34:35]
	v_pk_fma_f32 v[36:37], v[102:103], v[102:103], v[36:37]
	v_pk_fma_f32 v[34:35], v[88:89], v[88:89], v[34:35]
	v_pk_fma_f32 v[36:37], v[104:105], v[104:105], v[36:37]
	v_pk_fma_f32 v[34:35], v[90:91], v[90:91], v[34:35]
	v_pk_fma_f32 v[36:37], v[106:107], v[106:107], v[36:37]
	v_pk_fma_f32 v[34:35], v[92:93], v[92:93], v[34:35]
	v_pk_fma_f32 v[36:37], v[108:109], v[108:109], v[36:37]
	v_pk_fma_f32 v[34:35], v[94:95], v[94:95], v[34:35]
	v_pk_fma_f32 v[36:37], v[110:111], v[110:111], v[36:37]
	v_pk_fma_f32 v[34:35], v[96:97], v[96:97], v[34:35]
	v_pk_fma_f32 v[36:37], v[112:113], v[112:113], v[36:37]
	v_pk_fma_f32 v[34:35], v[98:99], v[98:99], v[34:35]
	v_pk_fma_f32 v[36:37], v[114:115], v[114:115], v[36:37]
	v_add_f32_e32 v34, v34, v35
	v_add_f32_e32 v36, v36, v37
	ds_bpermute_b32 v35, v51, v34
	ds_bpermute_b32 v37, v51, v36
	s_waitcnt lgkmcnt(0)
	v_add_f32_e32 v34, v34, v35
	v_add_f32_e32 v36, v36, v37
	ds_bpermute_b32 v35, v66, v34
	ds_bpermute_b32 v37, v66, v36
	s_waitcnt lgkmcnt(0)
	v_add_f32_e32 v34, v34, v35
	v_add_f32_e32 v36, v36, v37
	ds_bpermute_b32 v35, v67, v34
	ds_bpermute_b32 v37, v67, v36
	s_waitcnt lgkmcnt(0)
	v_add_f32_e32 v34, v34, v35
	v_add_f32_e32 v36, v36, v37
	ds_bpermute_b32 v35, v68, v34
	ds_bpermute_b32 v37, v68, v36
	s_waitcnt lgkmcnt(0)
	v_add_f32_e32 v34, v34, v35
	v_add_f32_e32 v36, v36, v37
	ds_bpermute_b32 v35, v69, v34
	ds_bpermute_b32 v37, v69, v36
	s_waitcnt lgkmcnt(0)
	v_add_f32_e32 v34, v34, v35
	v_add_f32_e32 v36, v36, v37
	ds_bpermute_b32 v35, v70, v34
	ds_bpermute_b32 v37, v70, v36
	s_waitcnt lgkmcnt(0)
	v_add_f32_e32 v34, v34, v35
	v_add_f32_e32 v36, v36, v37
	v_fmamk_f32 v34, v34, 0x3a800000, v74
	v_fmamk_f32 v36, v36, 0x3a800000, v74
	v_mul_f32_e32 v75, 0x4b800000, v34
	v_cmp_gt_f32_e32 vcc, s24, v34
	s_nop 1
	v_cndmask_b32_e32 v34, v34, v75, vcc
	v_rsq_f32_e32 v34, v34
	s_nop 0
	v_mul_f32_e32 v75, 0x45800000, v34
	v_cndmask_b32_e32 v34, v34, v75, vcc
	v_mov_b32_e32 v35, 0
	v_mul_f32_e32 v75, 0x4b800000, v36
	v_cmp_gt_f32_e32 vcc, s24, v36
	s_nop 1
	v_cndmask_b32_e32 v36, v36, v75, vcc
	v_rsq_f32_e32 v36, v36
	s_nop 0
	v_mul_f32_e32 v75, 0x45800000, v36
	v_cndmask_b32_e32 v36, v36, v75, vcc
	v_mov_b32_e32 v37, 0
	s_add_u32 s0, s19, 6
	s_lshl_b32 s0, s0, 11
	s_add_u32 s2, s72, s0
	s_addc_u32 s3, s73, 0
	v_pk_mul_f32 v[84:85], v[84:85], v[34:35] op_sel_hi:[1,0]
	v_pk_mul_f32 v[86:87], v[86:87], v[34:35] op_sel_hi:[1,0]
	v_pk_fma_f32 v[84:85], v[2:3], v[84:85], v[10:11]
	v_pk_fma_f32 v[86:87], v[4:5], v[86:87], v[12:13]
	v_cvt_pk_bf16_f32 v84, v84, v85
	v_cvt_pk_bf16_f32 v85, v86, v87
	global_store_dwordx2 v78, v[84:85], s[2:3] offset:0
	v_pk_mul_f32 v[88:89], v[88:89], v[34:35] op_sel_hi:[1,0]
	v_pk_mul_f32 v[90:91], v[90:91], v[34:35] op_sel_hi:[1,0]
	v_pk_fma_f32 v[88:89], v[6:7], v[88:89], v[14:15]
	v_pk_fma_f32 v[90:91], v[8:9], v[90:91], v[16:17]
	v_cvt_pk_bf16_f32 v88, v88, v89
	v_cvt_pk_bf16_f32 v89, v90, v91
	global_store_dwordx2 v78, v[88:89], s[2:3] offset:512
	v_pk_mul_f32 v[92:93], v[92:93], v[34:35] op_sel_hi:[1,0]
	v_pk_mul_f32 v[94:95], v[94:95], v[34:35] op_sel_hi:[1,0]
	v_pk_fma_f32 v[92:93], v[18:19], v[92:93], v[26:27]
	v_pk_fma_f32 v[94:95], v[20:21], v[94:95], v[28:29]
	v_cvt_pk_bf16_f32 v92, v92, v93
	v_cvt_pk_bf16_f32 v93, v94, v95
	global_store_dwordx2 v78, v[92:93], s[2:3] offset:1024
	v_pk_mul_f32 v[96:97], v[96:97], v[34:35] op_sel_hi:[1,0]
	v_pk_mul_f32 v[98:99], v[98:99], v[34:35] op_sel_hi:[1,0]
	v_pk_fma_f32 v[96:97], v[22:23], v[96:97], v[30:31]
	v_pk_fma_f32 v[98:99], v[24:25], v[98:99], v[32:33]
	v_cvt_pk_bf16_f32 v96, v96, v97
	v_cvt_pk_bf16_f32 v97, v98, v99
	global_store_dwordx2 v78, v[96:97], s[2:3] offset:1536
	s_add_u32 s0, s19, 7
	s_lshl_b32 s0, s0, 11
	s_add_u32 s2, s72, s0
	s_addc_u32 s3, s73, 0
	v_pk_mul_f32 v[100:101], v[100:101], v[36:37] op_sel_hi:[1,0]
	v_pk_mul_f32 v[102:103], v[102:103], v[36:37] op_sel_hi:[1,0]
	v_pk_fma_f32 v[100:101], v[2:3], v[100:101], v[10:11]
	v_pk_fma_f32 v[102:103], v[4:5], v[102:103], v[12:13]
	v_cvt_pk_bf16_f32 v100, v100, v101
	v_cvt_pk_bf16_f32 v101, v102, v103
	global_store_dwordx2 v78, v[100:101], s[2:3] offset:0
	v_pk_mul_f32 v[104:105], v[104:105], v[36:37] op_sel_hi:[1,0]
	v_pk_mul_f32 v[106:107], v[106:107], v[36:37] op_sel_hi:[1,0]
	v_pk_fma_f32 v[104:105], v[6:7], v[104:105], v[14:15]
	v_pk_fma_f32 v[106:107], v[8:9], v[106:107], v[16:17]
	v_cvt_pk_bf16_f32 v104, v104, v105
	v_cvt_pk_bf16_f32 v105, v106, v107
	global_store_dwordx2 v78, v[104:105], s[2:3] offset:512
	v_pk_mul_f32 v[108:109], v[108:109], v[36:37] op_sel_hi:[1,0]
	v_pk_mul_f32 v[110:111], v[110:111], v[36:37] op_sel_hi:[1,0]
	v_pk_fma_f32 v[108:109], v[18:19], v[108:109], v[26:27]
	v_pk_fma_f32 v[110:111], v[20:21], v[110:111], v[28:29]
	v_cvt_pk_bf16_f32 v108, v108, v109
	v_cvt_pk_bf16_f32 v109, v110, v111
	global_store_dwordx2 v78, v[108:109], s[2:3] offset:1024
	v_pk_mul_f32 v[112:113], v[112:113], v[36:37] op_sel_hi:[1,0]
	v_pk_mul_f32 v[114:115], v[114:115], v[36:37] op_sel_hi:[1,0]
	v_pk_fma_f32 v[112:113], v[22:23], v[112:113], v[30:31]
	v_pk_fma_f32 v[114:115], v[24:25], v[114:115], v[32:33]
	v_cvt_pk_bf16_f32 v112, v112, v113
	v_cvt_pk_bf16_f32 v113, v114, v115
	global_store_dwordx2 v78, v[112:113], s[2:3] offset:1536
	s_nop 1
	s_branch .LBB0_153
